# attention: K/V staging of tile t+1 and loads of tile t+2 moved from the top of the tile iteration to its end (before the next barrier); on top of v44
# speedup vs baseline: 1.0008x; 1.0008x over previous
; #define LAS __attribute__((address_space(3)))
; #define LDS_BARRIER() asm volatile("s_waitcnt lgkmcnt(0)\n\ts_barrier" ::: "memory")
; __device__ __forceinline__ void attn_phase(LAS unsigned char* lds, const bf16_t* QKV, const float* kmean, const float* biasT, bf16_t* O, int G, int wg) {
;     ...
;             LDS_BARRIER();
;             const int nxt = (cur == 2) ? 0 : cur + 1;
;             if (ti + 1 < nTiles) { ATT_STAGE(nxt); if (ti + 2 < nTiles) ATT_LOAD(ti + 2); }
;             const LAS unsigned char* sb = lds + cur * STAGE;
;             if (pend) { ATT_PV(lds + pend_buf * STAGE); pend = false; }
.LBB0_1351:
	s_add_i32 s45, s59, 1
	s_cmp_lg_u32 s59, 2
	s_waitcnt lgkmcnt(0)
	s_barrier
	v_add_co_u32_e64 v128, s[0:1], s57, 4
	s_cselect_b32 s58, s45, 0
.LBB0_1354:
	s_and_saveexec_b64 s[44:45], s[38:39]
	s_cbranch_execz .LBB0_1356
	s_setprio 2
	v_mad_u64_u32 v[132:133], s[48:49], v232, s93, v[168:169]
	v_add_u32_e32 v133, 0x4000, v132
	ds_read2_b64 v[128:131], v133 offset1:4
	s_waitcnt lgkmcnt(0)
	v_mfma_f32_16x16x32_bf16 v[92:95], v[128:131], v[112:115], v[92:95]
	v_mfma_f32_16x16x32_bf16 v[60:63], v[128:131], v[120:123], v[60:63]
	ds_read2_b64 v[128:131], v133 offset0:8 offset1:12
	v_add_u32_e32 v133, 0x4800, v132
	s_waitcnt lgkmcnt(0)
	v_mfma_f32_16x16x32_bf16 v[92:95], v[128:131], v[116:119], v[92:95]
	v_mfma_f32_16x16x32_bf16 v[60:63], v[128:131], v[124:127], v[60:63]
	ds_read2_b64 v[128:131], v133 offset0:16 offset1:20
	s_waitcnt lgkmcnt(0)
	v_mfma_f32_16x16x32_bf16 v[88:91], v[128:131], v[112:115], v[88:91]
	v_mfma_f32_16x16x32_bf16 v[56:59], v[128:131], v[120:123], v[56:59]
	ds_read2_b64 v[128:131], v133 offset0:24 offset1:28
	s_waitcnt lgkmcnt(0)
	v_mfma_f32_16x16x32_bf16 v[88:91], v[128:131], v[116:119], v[88:91]
	v_mfma_f32_16x16x32_bf16 v[56:59], v[128:131], v[124:127], v[56:59]
	v_add_u32_e32 v133, 0x5000, v132
	ds_read2_b64 v[128:131], v133 offset0:32 offset1:36
	s_waitcnt lgkmcnt(0)
	v_mfma_f32_16x16x32_bf16 v[84:87], v[128:131], v[112:115], v[84:87]
	v_mfma_f32_16x16x32_bf16 v[52:55], v[128:131], v[120:123], v[52:55]
	ds_read2_b64 v[128:131], v133 offset0:40 offset1:44
	v_add_u32_e32 v133, 0x5800, v132
	s_waitcnt lgkmcnt(0)
	v_mfma_f32_16x16x32_bf16 v[84:87], v[128:131], v[116:119], v[84:87]
	v_mfma_f32_16x16x32_bf16 v[52:55], v[128:131], v[124:127], v[52:55]
	ds_read2_b64 v[128:131], v133 offset0:48 offset1:52
	s_waitcnt lgkmcnt(0)
	v_mfma_f32_16x16x32_bf16 v[80:83], v[128:131], v[112:115], v[80:83]
	v_mfma_f32_16x16x32_bf16 v[48:51], v[128:131], v[120:123], v[48:51]
	ds_read2_b64 v[128:131], v133 offset0:56 offset1:60
	s_waitcnt lgkmcnt(0)
	v_mfma_f32_16x16x32_bf16 v[80:83], v[128:131], v[116:119], v[80:83]
	v_mfma_f32_16x16x32_bf16 v[48:51], v[128:131], v[124:127], v[48:51]
	v_add_u32_e32 v133, 0x6000, v132
	ds_read2_b64 v[128:131], v133 offset0:64 offset1:68
	s_waitcnt lgkmcnt(0)
	v_mfma_f32_16x16x32_bf16 v[76:79], v[128:131], v[112:115], v[76:79]
	v_mfma_f32_16x16x32_bf16 v[44:47], v[128:131], v[120:123], v[44:47]
	ds_read2_b64 v[128:131], v133 offset0:72 offset1:76
	v_add_u32_e32 v133, 0x6800, v132
	s_waitcnt lgkmcnt(0)
	v_mfma_f32_16x16x32_bf16 v[76:79], v[128:131], v[116:119], v[76:79]
	v_mfma_f32_16x16x32_bf16 v[44:47], v[128:131], v[124:127], v[44:47]
	ds_read2_b64 v[128:131], v133 offset0:80 offset1:84
	s_waitcnt lgkmcnt(0)
	v_mfma_f32_16x16x32_bf16 v[72:75], v[128:131], v[112:115], v[72:75]
	v_mfma_f32_16x16x32_bf16 v[40:43], v[128:131], v[120:123], v[40:43]
	ds_read2_b64 v[128:131], v133 offset0:88 offset1:92
	s_waitcnt lgkmcnt(0)
	v_mfma_f32_16x16x32_bf16 v[72:75], v[128:131], v[116:119], v[72:75]
	v_mfma_f32_16x16x32_bf16 v[40:43], v[128:131], v[124:127], v[40:43]
	v_add_u32_e32 v133, 0x7000, v132
	ds_read2_b64 v[128:131], v133 offset0:96 offset1:100
	v_add_u32_e32 v132, 0x7800, v132
	s_waitcnt lgkmcnt(0)
	v_mfma_f32_16x16x32_bf16 v[68:71], v[128:131], v[112:115], v[68:71]
	v_mfma_f32_16x16x32_bf16 v[36:39], v[128:131], v[120:123], v[36:39]
	ds_read2_b64 v[128:131], v133 offset0:104 offset1:108
	s_waitcnt lgkmcnt(0)
	v_mfma_f32_16x16x32_bf16 v[68:71], v[128:131], v[116:119], v[68:71]
	v_mfma_f32_16x16x32_bf16 v[36:39], v[128:131], v[124:127], v[36:39]
	ds_read2_b64 v[128:131], v132 offset0:112 offset1:116
	s_waitcnt lgkmcnt(0)
	v_mfma_f32_16x16x32_bf16 v[64:67], v[128:131], v[112:115], v[64:67]
	v_mfma_f32_16x16x32_bf16 v[32:35], v[128:131], v[120:123], v[32:35]
	ds_read2_b64 v[128:131], v132 offset0:120 offset1:124
	s_waitcnt lgkmcnt(0)
	v_mfma_f32_16x16x32_bf16 v[64:67], v[128:131], v[116:119], v[64:67]
	v_mfma_f32_16x16x32_bf16 v[32:35], v[128:131], v[124:127], v[32:35]

; #define LAS __attribute__((address_space(3)))
; __device__ __forceinline__ void attn_phase(LAS unsigned char* lds, const bf16_t* QKV, const float* kmean, const float* biasT, bf16_t* O, int G, int wg) {
;     ...
;             const int nxt = (cur == 2) ? 0 : cur + 1;
;             if (ti + 1 < nTiles) { ATT_STAGE(nxt); if (ti + 2 < nTiles) ATT_LOAD(ti + 2); }
;             const LAS unsigned char* sb = lds + cur * STAGE;
;             if (pend) { ATT_PV(lds + pend_buf * STAGE); pend = false; }
;             const int cur_ = cur; cur = nxt;
.LBB0_1372:
	s_or_b64 exec, exec, s[48:49]
	s_add_i32 s45, s57, 5
	s_add_i32 s44, s57, 4
	s_cmp_ge_u32 s45, s55
	s_cbranch_scc1 .Lst_skip
	s_mul_i32 s45, s58, 0x8800
	s_add_i32 s45, s45, 0
	v_add_u32_e32 v128, s45, v208
	v_add_u32_e32 v129, v128, v217
	v_add_u32_e32 v128, v128, v218
	s_waitcnt vmcnt(3)
	ds_write_b128 v128, v[96:99]
	v_add3_u32 v128, s45, v219, v220
	s_add_i32 s45, s57, 6
	s_cmp_ge_u32 s45, s55
	s_waitcnt vmcnt(2)
	ds_write_b128 v129, v[100:103]
	s_waitcnt vmcnt(1)
	ds_write_b16 v128, v104 offset:16384
	s_waitcnt vmcnt(0)
	ds_write_b16 v128, v108 offset:17472
	ds_write_b16_d16_hi v128, v104 offset:16520
	ds_write_b16_d16_hi v128, v108 offset:17608
	ds_write_b16 v128, v105 offset:16656
	ds_write_b16 v128, v109 offset:17744
	ds_write_b16_d16_hi v128, v105 offset:16792
	ds_write_b16_d16_hi v128, v109 offset:17880
	ds_write_b16 v128, v106 offset:16928
	ds_write_b16 v128, v110 offset:18016
	ds_write_b16_d16_hi v128, v106 offset:17064
	ds_write_b16_d16_hi v128, v110 offset:18152
	ds_write_b16 v128, v107 offset:17200
	ds_write_b16 v128, v111 offset:18288
	ds_write_b16_d16_hi v128, v107 offset:17336
	ds_write_b16_d16_hi v128, v111 offset:18424
	s_cbranch_scc1 .Lst_skip
	s_add_i32 s48, s57, 2
	s_lshr_b32 s49, s48, 2
	s_and_b32 s48, s48, 3
	s_cmp_lt_u32 s44, 2
	s_cselect_b32 s44, s54, s49
	s_cselect_b32 s45, s45, s48
	s_lshl_b32 s44, s44, 8
	s_lshl_b32 s45, s45, 6
	s_add_i32 s44, s44, s45
	s_ashr_i32 s45, s44, 31
	s_add_u32 s44, s44, s46
	s_addc_u32 s45, s45, 0
	v_lshl_add_u64 v[96:97], s[44:45], 0, v[146:147]
	v_mad_u64_u32 v[100:101], s[48:49], v96, s89, v[184:185]
	v_mad_i32_i24 v101, v97, s89, v101
	v_or_b32_e32 v98, s44, v144
	v_mov_b64_e32 v[96:97], s[14:15]
	v_mad_u64_u32 v[96:97], s[48:49], v98, s89, v[96:97]
	v_mov_b32_e32 v98, 0x1800
	v_mad_i32_i24 v97, s45, v98, v97
	v_lshl_add_u64 v[96:97], v[96:97], 0, s[16:17]
	v_lshl_add_u64 v[104:105], v[148:149], 1, v[96:97]
	v_lshl_add_u64 v[108:109], v[104:105], 0, s[94:95]
	v_add_co_u32_e32 v104, vcc, 0x1000, v104
	global_load_dwordx4 v[96:99], v[100:101], off offset:2064
	s_nop 0
	global_load_dwordx4 v[100:103], v[100:101], off offset:2048
	v_addc_co_u32_e32 v105, vcc, 0, v105, vcc
	global_load_dwordx4 v[104:107], v[104:105], off
	s_nop 0
	global_load_dwordx4 v[108:111], v[108:109], off offset:16
.Lst_skip:
	s_add_i32 s57, s57, 1
	s_add_i32 s56, s56, 64
	s_cmp_eq_u32 s47, s57
	s_cbranch_scc1 .LBB0_1374
	s_mov_b32 s59, s58
	s_branch .LBB0_1351
